# rowpass: contiguous 128-row block per workgroup (modulation vectors reloaded twice per phase) + 2-row-ahead prefetch with counted vmcnt, no store drains
# speedup vs baseline: 1.0208x; 1.0022x over previous
.LBB0_500:
	v_readlane_b32 s1, v254, 54
	v_mbcnt_lo_u32_b32 v0, -1, 0
	v_mbcnt_hi_u32_b32 v0, -1, v0
	v_lshl_add_u32 v0, s1, 6, v0
	v_readlane_b32 s1, v254, 57
	v_ashrrev_i32_e32 v2, 6, v0
	s_nop 0
	v_add_u32_e32 v152, s1, v2
	s_cmp_lg_u32 s76, 0x800
	s_cbranch_scc1 .Lrp_nx0
	v_lshl_add_u32 v152, s1, 4, v2
.Lrp_nx0:
	v_cmp_gt_i32_e32 vcc, s15, v152
	s_and_saveexec_b64 s[28:29], vcc
	s_cbranch_execz .LBB0_580
	v_lshlrev_b32_e32 v0, 2, v0
	s_cmp_lg_u64 s[6:7], 0
	s_waitcnt vmcnt(0)
	v_and_b32_e32 v68, 0xfc, v0
	s_cselect_b64 s[8:9], -1, 0
	s_cmp_eq_u64 s[6:7], 0
	v_lshlrev_b32_e32 v32, 2, v68
	s_cbranch_scc1 .LBB0_510
	global_load_dwordx4 v[4:7], v32, s[2:3]
	s_cmp_lg_u64 s[46:47], 0
	s_cselect_b64 s[54:55], -1, 0
	s_cmp_eq_u64 s[46:47], 0
	s_cbranch_scc1 .LBB0_511

.LBB0_524:
	v_add_u32_e32 v70, s76, v152
	s_cmp_lg_u32 s76, 0x800
	s_cbranch_scc1 .Lrp_nxa
	v_add_u32_e32 v208, 8, v152
	v_xor_b32_e32 v209, v208, v152
	v_lshrrev_b32_e32 v209, 7, v209
	v_cmp_ne_u32_e64 s[100:101], 0, v209
	v_lshrrev_b32_e32 v209, 7, v152
	v_and_b32_e32 v214, 7, v152
	v_lshl_add_u32 v209, v209, 3, v214
	v_add_u32_e32 v209, s84, v209
	v_cndmask_b32_e64 v208, v208, v209, s[100:101]
	v_cmp_gt_i32_e64 s[100:101], s84, v152
	s_nop 1
	v_cndmask_b32_e64 v70, v70, v208, s[100:101]
.Lrp_nxa:
	s_waitcnt vmcnt(0)
	v_mov_b64_e32 v[54:55], v[38:39]
	v_mov_b64_e32 v[58:59], v[42:43]
	v_mov_b64_e32 v[62:63], v[46:47]
	v_mov_b64_e32 v[66:67], v[50:51]
	v_cmp_gt_i32_e32 vcc, s15, v70
	v_mov_b64_e32 v[52:53], v[36:37]
	v_mov_b64_e32 v[56:57], v[40:41]
	v_mov_b64_e32 v[60:61], v[44:45]
	v_mov_b64_e32 v[64:65], v[48:49]
	v_mov_b64_e32 v[168:169], v[154:155]
	v_mov_b64_e32 v[166:167], v[156:157]
	v_mov_b64_e32 v[164:165], v[158:159]
	v_mov_b64_e32 v[162:163], v[160:161]
	s_and_saveexec_b64 s[10:11], vcc
	s_cbranch_execz .LBB0_529
	v_add_u32_e32 v0, 0xffff8000, v70
	v_cmp_gt_i32_e64 s[42:43], s84, v70
	v_ashrrev_i32_e32 v71, 31, v70
	v_mov_b32_e32 v3, s59
	v_cndmask_b32_e64 v52, v0, v70, s[42:43]
	v_mov_b32_e32 v0, s57
	v_cndmask_b32_e64 v53, 0, v71, s[42:43]
	v_cndmask_b32_e64 v55, v0, v3, s[42:43]
	v_mov_b32_e32 v0, s56
	v_mov_b32_e32 v3, s58
	v_cndmask_b32_e64 v54, v0, v3, s[42:43]
	v_lshlrev_b64 v[52:53], 12, v[52:53]
	v_lshl_add_u64 v[52:53], v[54:55], 0, v[52:53]
	v_mov_b32_e32 v3, v1
	v_lshl_add_u64 v[52:53], v[52:53], 0, v[2:3]
	global_load_dwordx4 v[64:67], v[52:53], off nt
	global_load_dwordx4 v[60:63], v[52:53], off offset:1024 nt
	global_load_dwordx4 v[56:59], v[52:53], off offset:2048 nt
	s_nop 0
	global_load_dwordx4 v[52:55], v[52:53], off offset:3072 nt
	s_and_b64 vcc, exec, s[38:39]
	v_mov_b64_e32 v[162:163], v[160:161]
	v_mov_b64_e32 v[164:165], v[158:159]
	v_mov_b64_e32 v[166:167], v[156:157]
	v_mov_b64_e32 v[168:169], v[154:155]
	s_cbranch_vccnz .LBB0_529
	v_mov_b64_e32 v[162:163], v[160:161]
	v_mov_b64_e32 v[164:165], v[158:159]
	v_mov_b64_e32 v[166:167], v[156:157]
	v_mov_b64_e32 v[168:169], v[154:155]
	s_and_saveexec_b64 s[8:9], s[42:43]
	s_cbranch_execz .LBB0_528
	v_readlane_b32 s42, v255, 16
	v_lshlrev_b64 v[70:71], 11, v[70:71]
	v_readlane_b32 s43, v255, 17
	v_lshlrev_b32_e32 v0, 1, v68
	s_nop 0
	v_lshl_add_u64 v[70:71], s[42:43], 0, v[70:71]
	v_lshl_add_u64 v[70:71], v[70:71], 0, v[0:1]
	global_load_dwordx2 v[162:163], v[70:71], off
	global_load_dwordx2 v[164:165], v[70:71], off offset:512
	global_load_dwordx2 v[166:167], v[70:71], off offset:1024
	global_load_dwordx2 v[168:169], v[70:71], off offset:1536

.LBB0_529:
	s_or_b64 exec, exec, s[10:11]
	s_and_b64 s[8:9], s[44:45], exec
	v_readlane_b32 s8, v255, 16
	v_lshlrev_b32_e32 v0, 1, v68
	v_readlane_b32 s9, v255, 17
	s_cselect_b32 s63, 2, 3
	v_lshl_add_u64 v[68:69], s[6:7], 0, v[0:1]
	v_lshl_add_u64 v[170:171], s[8:9], 0, v[0:1]
	s_lshl_b64 s[8:9], s[52:53], 2
	s_add_u32 s30, s30, s8
	s_addc_u32 s31, s31, s9
	s_mov_b64 s[8:9], 0x1c700004
	v_lshl_add_u64 v[174:175], v[68:69], 0, s[8:9]
	s_mov_b64 s[8:9], 0x1c700204
	v_lshl_add_u64 v[176:177], v[68:69], 0, s[8:9]
	s_mov_b64 s[8:9], 0x1c700404
	v_lshl_add_u64 v[178:179], v[68:69], 0, s[8:9]
	s_mov_b64 s[8:9], 0x1c700604
	v_lshl_add_u64 v[180:181], v[68:69], 0, s[8:9]
	v_mov_b64_e32 v[70:71], v[30:31]
	v_mov_b64_e32 v[74:75], v[22:23]
	v_mov_b64_e32 v[78:79], v[14:15]
	v_mov_b64_e32 v[82:83], v[6:7]
	v_mov_b64_e32 v[86:87], v[30:31]
	v_mov_b64_e32 v[90:91], v[22:23]
	v_mov_b64_e32 v[94:95], v[14:15]
	v_mov_b64_e32 v[98:99], v[6:7]
	v_mov_b64_e32 v[102:103], v[30:31]
	v_mov_b64_e32 v[106:107], v[22:23]
	v_mov_b64_e32 v[110:111], v[14:15]
	v_mov_b64_e32 v[114:115], v[6:7]
	s_mov_b32 s19, s18
	s_mov_b32 s10, s18
	s_mov_b32 s11, s18
	v_lshl_add_u64 v[172:173], s[46:47], 0, v[0:1]
	v_mov_b32_e32 v192, -1
	s_mov_b64 s[44:45], 0
	v_mov_b64_e32 v[68:69], v[28:29]
	v_mov_b64_e32 v[72:73], v[20:21]
	v_mov_b64_e32 v[76:77], v[12:13]
	v_mov_b64_e32 v[80:81], v[4:5]
	v_mov_b64_e32 v[84:85], v[28:29]
	v_mov_b64_e32 v[88:89], v[20:21]
	v_mov_b64_e32 v[92:93], v[12:13]
	v_mov_b64_e32 v[96:97], v[4:5]
	v_mov_b64_e32 v[100:101], v[28:29]
	v_mov_b64_e32 v[104:105], v[20:21]
	v_mov_b64_e32 v[108:109], v[12:13]
	v_mov_b64_e32 v[112:113], v[4:5]
	s_waitcnt vmcnt(0)
	v_mov_b64_e32 v[130:131], v[54:55]
	v_mov_b64_e32 v[126:127], v[58:59]
	v_mov_b64_e32 v[122:123], v[62:63]
	v_mov_b64_e32 v[118:119], v[66:67]
	v_mov_b64_e32 v[128:129], v[52:53]
	v_mov_b64_e32 v[124:125], v[56:57]
	v_mov_b64_e32 v[120:121], v[60:61]
	v_mov_b64_e32 v[116:117], v[64:65]
	v_mov_b64_e32 v[190:191], v[168:169]
	v_mov_b64_e32 v[188:189], v[166:167]
	v_mov_b64_e32 v[186:187], v[164:165]
	v_mov_b64_e32 v[182:183], v[162:163]
	s_branch .LBB0_531

.LBB0_531:
	v_add_u32_e32 v184, s76, v152
	s_cmp_lg_u32 s76, 0x800
	s_cbranch_scc1 .Lrp_nxb
	v_add_u32_e32 v208, 8, v152
	v_xor_b32_e32 v209, v208, v152
	v_lshrrev_b32_e32 v209, 7, v209
	v_cmp_ne_u32_e64 s[100:101], 0, v209
	v_lshrrev_b32_e32 v209, 7, v152
	v_and_b32_e32 v214, 7, v152
	v_lshl_add_u32 v209, v209, 3, v214
	v_add_u32_e32 v209, s84, v209
	v_cndmask_b32_e64 v208, v208, v209, s[100:101]
	v_cmp_gt_i32_e64 s[100:101], s84, v152
	s_nop 1
	v_cndmask_b32_e64 v184, v184, v208, s[100:101]
.Lrp_nxb:
	v_add_u32_e32 v132, s76, v184
	s_cmp_lg_u32 s76, 0x800
	s_cbranch_scc1 .Lrp_nxc
	v_add_u32_e32 v208, 8, v184
	v_xor_b32_e32 v209, v208, v184
	v_lshrrev_b32_e32 v209, 7, v209
	v_cmp_ne_u32_e64 s[100:101], 0, v209
	v_lshrrev_b32_e32 v209, 7, v184
	v_and_b32_e32 v214, 7, v184
	v_lshl_add_u32 v209, v209, 3, v214
	v_add_u32_e32 v209, s84, v209
	v_cndmask_b32_e64 v208, v208, v209, s[100:101]
	v_cmp_gt_i32_e64 s[100:101], s84, v184
	s_nop 1
	v_cndmask_b32_e64 v132, v132, v208, s[100:101]
.Lrp_nxc:
	s_cmp_eq_u64 s[40:41], 0
	s_cbranch_scc0 .Lrp_top4
	s_waitcnt vmcnt(8)
	s_branch .Lrp_topd
.Lrp_top4:
	s_waitcnt vmcnt(4)
.Lrp_topd:
	v_mov_b64_e32 v[54:55], v[130:131]
	v_mov_b64_e32 v[58:59], v[126:127]
	v_mov_b64_e32 v[62:63], v[122:123]
	v_mov_b64_e32 v[66:67], v[118:119]
	v_mov_b64_e32 v[52:53], v[128:129]
	v_mov_b64_e32 v[56:57], v[124:125]
	v_mov_b64_e32 v[60:61], v[120:121]
	v_mov_b64_e32 v[64:65], v[116:117]
	v_mov_b64_e32 v[168:169], v[190:191]
	v_mov_b64_e32 v[166:167], v[188:189]
	v_mov_b64_e32 v[164:165], v[186:187]
	v_mov_b64_e32 v[162:163], v[182:183]
	v_cmp_gt_i32_e32 vcc, s15, v132
	s_and_saveexec_b64 s[46:47], vcc
	s_cbranch_execz .LBB0_536
	v_add_u32_e32 v0, 0xffff8000, v132
	v_cmp_gt_i32_e64 s[42:43], s84, v132
	v_ashrrev_i32_e32 v133, 31, v132
	v_mov_b32_e32 v3, s59
	v_cndmask_b32_e64 v116, v0, v132, s[42:43]
	v_mov_b32_e32 v0, s57
	v_cndmask_b32_e64 v117, 0, v133, s[42:43]
	v_cndmask_b32_e64 v119, v0, v3, s[42:43]
	v_mov_b32_e32 v0, s56
	v_mov_b32_e32 v3, s58
	v_cndmask_b32_e64 v118, v0, v3, s[42:43]
	v_lshlrev_b64 v[116:117], 12, v[116:117]
	v_lshl_add_u64 v[116:117], v[118:119], 0, v[116:117]
	v_mov_b32_e32 v3, v1
	v_lshl_add_u64 v[128:129], v[116:117], 0, v[2:3]
	global_load_dwordx4 v[116:119], v[128:129], off nt
	global_load_dwordx4 v[120:123], v[128:129], off offset:1024 nt
	global_load_dwordx4 v[124:127], v[128:129], off offset:2048 nt
	s_nop 0
	global_load_dwordx4 v[128:131], v[128:129], off offset:3072 nt
	s_and_b64 vcc, exec, s[38:39]
	v_mov_b64_e32 v[182:183], v[162:163]
	v_mov_b64_e32 v[186:187], v[164:165]
	v_mov_b64_e32 v[188:189], v[166:167]
	v_mov_b64_e32 v[190:191], v[168:169]
	s_cbranch_vccnz .LBB0_536
	v_mov_b64_e32 v[182:183], v[162:163]
	v_mov_b64_e32 v[186:187], v[164:165]
	v_mov_b64_e32 v[188:189], v[166:167]
	v_mov_b64_e32 v[190:191], v[168:169]
	s_and_saveexec_b64 s[8:9], s[42:43]
	s_cbranch_execz .LBB0_535
	v_lshlrev_b64 v[132:133], 11, v[132:133]
	v_lshl_add_u64 v[132:133], v[170:171], 0, v[132:133]
	global_load_dwordx2 v[182:183], v[132:133], off
	global_load_dwordx2 v[186:187], v[132:133], off offset:512
	global_load_dwordx2 v[188:189], v[132:133], off offset:1024
	global_load_dwordx2 v[190:191], v[132:133], off offset:1536

.LBB0_576:
	v_pk_mul_f32 v[202:203], v[140:141], v[140:141]
	v_pk_mul_f32 v[204:205], v[136:137], v[136:137]
	v_pk_mul_f32 v[198:199], v[142:143], v[142:143]
	v_pk_mul_f32 v[200:201], v[138:139], v[138:139]
	v_mov_b32_e32 v206, v202
	v_mov_b32_e32 v207, v204
	v_mov_b32_e32 v204, v203
	v_pk_add_f32 v[202:203], v[206:207], v[204:205]
	v_mov_b32_e32 v204, v198
	v_mov_b32_e32 v205, v200
	v_pk_mul_f32 v[148:149], v[148:149], v[148:149]
	v_pk_mul_f32 v[196:197], v[132:133], v[132:133]
	v_pk_add_f32 v[202:203], v[204:205], v[202:203]
	v_mov_b32_e32 v200, v199
	v_pk_mul_f32 v[150:151], v[150:151], v[150:151]
	v_pk_mul_f32 v[194:195], v[134:135], v[134:135]
	v_pk_add_f32 v[198:199], v[200:201], v[202:203]
	v_mov_b32_e32 v200, v148
	v_mov_b32_e32 v201, v196
	v_mov_b32_e32 v196, v149
	v_pk_add_f32 v[148:149], v[200:201], v[196:197]
	v_mov_b32_e32 v196, v150
	v_mov_b32_e32 v197, v194
	v_pk_add_f32 v[148:149], v[196:197], v[148:149]
	v_mov_b32_e32 v194, v151
	v_pk_add_f32 v[148:149], v[194:195], v[148:149]
	v_add_f32_e32 v0, v198, v199
	v_add_f32_e32 v0, v149, v0
	v_add_f32_e32 v0, v148, v0
	s_cmp_eq_u32 s98, 0
	s_cbranch_scc1 .Lrp_skip_w3
	s_waitcnt vmcnt(0)
.Lrp_skip_w3:
	v_pk_add_f32 v[150:151], v[114:115], 1.0 op_sel_hi:[1,0]
	v_pk_add_f32 v[194:195], v[112:113], 1.0 op_sel_hi:[1,0]
	v_add_f32_dpp v0, v0, v0 quad_perm:[1,0,3,2] row_mask:0xf bank_mask:0xf bound_ctrl:1
	s_nop 1
	v_add_f32_dpp v0, v0, v0 quad_perm:[2,3,0,1] row_mask:0xf bank_mask:0xf bound_ctrl:1
	s_nop 1
	v_add_f32_dpp v0, v0, v0 row_half_mirror row_mask:0xf bank_mask:0xf bound_ctrl:1
	s_nop 1
	v_add_f32_dpp v0, v0, v0 row_mirror row_mask:0xf bank_mask:0xf bound_ctrl:1
	s_nop 0
	v_readlane_b32 s42, v0, 16
	v_readlane_b32 s43, v0, 48
	v_readlane_b32 s8, v0, 0
	v_readlane_b32 s9, v0, 32
	v_mov_b32_e32 v148, s42
	v_mov_b32_e32 v149, s43
	v_pk_add_f32 v[148:149], s[8:9], v[148:149]
	s_nop 0
	v_add_f32_e32 v0, v148, v149
	v_fmamk_f32 v0, v0, 0x3a800000, v213
	v_rsq_f32_e32 v0, v0
	v_lshlrev_b64 v[148:149], 11, v[152:153]
	v_pk_mul_f32 v[142:143], v[142:143], v[0:1] op_sel_hi:[1,0]
	v_pk_mul_f32 v[140:141], v[140:141], v[0:1] op_sel_hi:[1,0]
	v_pk_mul_f32 v[142:143], v[10:11], v[142:143]
	v_pk_mul_f32 v[140:141], v[8:9], v[140:141]
	v_pk_fma_f32 v[142:143], v[150:151], v[142:143], v[98:99]
	v_pk_fma_f32 v[140:141], v[194:195], v[140:141], v[96:97]
	v_pk_mul_f32 v[136:137], v[136:137], v[0:1] op_sel_hi:[1,0]
	v_cvt_pk_bf16_f32 v140, v140, v141
	v_cvt_pk_bf16_f32 v141, v142, v143
	v_lshl_add_u64 v[142:143], v[172:173], 0, v[148:149]
	v_pk_mul_f32 v[138:139], v[138:139], v[0:1] op_sel_hi:[1,0]
	v_pk_mul_f32 v[136:137], v[16:17], v[136:137]
	v_pk_add_f32 v[148:149], v[108:109], 1.0 op_sel_hi:[1,0]
	global_store_dwordx2 v[142:143], v[140:141], off
	v_pk_mul_f32 v[138:139], v[18:19], v[138:139]
	v_pk_add_f32 v[140:141], v[110:111], 1.0 op_sel_hi:[1,0]
	v_pk_fma_f32 v[136:137], v[148:149], v[136:137], v[92:93]
	v_pk_fma_f32 v[138:139], v[140:141], v[138:139], v[94:95]
	v_cvt_pk_bf16_f32 v136, v136, v137
	v_pk_mul_f32 v[134:135], v[134:135], v[0:1] op_sel_hi:[1,0]
	v_cvt_pk_bf16_f32 v137, v138, v139
	v_pk_mul_f32 v[132:133], v[132:133], v[0:1] op_sel_hi:[1,0]
	global_store_dwordx2 v[142:143], v[136:137], off offset:512
	v_pk_mul_f32 v[132:133], v[24:25], v[132:133]
	v_pk_mul_f32 v[134:135], v[26:27], v[134:135]
	v_pk_add_f32 v[136:137], v[106:107], 1.0 op_sel_hi:[1,0]
	v_pk_add_f32 v[138:139], v[104:105], 1.0 op_sel_hi:[1,0]
	v_pk_fma_f32 v[134:135], v[136:137], v[134:135], v[90:91]
	v_pk_fma_f32 v[132:133], v[138:139], v[132:133], v[88:89]
	v_pk_add_f32 v[138:139], v[100:101], 1.0 op_sel_hi:[1,0]
	v_cvt_pk_bf16_f32 v132, v132, v133
	v_cvt_pk_bf16_f32 v133, v134, v135
	v_pk_mul_f32 v[134:135], v[144:145], v[0:1] op_sel_hi:[1,0]
	global_store_dwordx2 v[142:143], v[132:133], off offset:1024
	v_pk_mul_f32 v[132:133], v[146:147], v[0:1] op_sel_hi:[1,0]
	v_pk_mul_f32 v[134:135], v[32:33], v[134:135]
	v_pk_mul_f32 v[132:133], v[34:35], v[132:133]
	v_pk_add_f32 v[136:137], v[102:103], 1.0 op_sel_hi:[1,0]
	v_pk_fma_f32 v[134:135], v[138:139], v[134:135], v[84:85]
	v_pk_fma_f32 v[132:133], v[136:137], v[132:133], v[86:87]
	v_cvt_pk_bf16_f32 v134, v134, v135
	s_nop 0
	v_cvt_pk_bf16_f32 v135, v132, v133
	global_store_dwordx2 v[142:143], v[134:135], off offset:1536
.LBB0_577:
	v_cmp_gt_i32_e64 s[42:43], s15, v184
	v_cmp_le_i32_e32 vcc, s15, v184
	s_and_saveexec_b64 s[8:9], s[42:43]
	s_cbranch_execz .LBB0_530
	v_mov_b64_e32 v[36:37], v[52:53]
	v_mov_b64_e32 v[40:41], v[56:57]
	v_mov_b64_e32 v[44:45], v[60:61]
	v_mov_b64_e32 v[48:49], v[64:65]
	v_mov_b64_e32 v[38:39], v[54:55]
	v_mov_b64_e32 v[42:43], v[58:59]
	v_mov_b64_e32 v[46:47], v[62:63]
	v_mov_b64_e32 v[50:51], v[66:67]
	v_mov_b64_e32 v[154:155], v[168:169]
	v_mov_b64_e32 v[156:157], v[166:167]
	v_mov_b64_e32 v[158:159], v[164:165]
	v_mov_b64_e32 v[160:161], v[162:163]
	v_mov_b32_e32 v152, v184
	s_branch .LBB0_530
